# exchange polls: the timeout clock read (s_memrealtime) requested together with the poll load and waited for only after a failed poll, not before the first poll
# baseline (speedup 1.0000x reference)
.LBB0_595:
	s_or_b64 exec, exec, s[18:19]
	s_cmp_lt_u32 s47, 64
	s_cselect_b64 s[20:21], -1, 0
	s_cmp_gt_u32 s47, 63
	s_cbranch_scc1 .LBB0_611
	s_memrealtime s[18:19]
	s_lshl_b32 s26, s14, 6
	s_ashr_i32 s27, s26, 31
	s_lshl_b64 s[26:27], s[26:27], 2
	s_add_u32 s26, s0, s26
	s_addc_u32 s27, s17, s27
	v_mov_b32_e32 v193, 0
	v_mov_b64_e32 v[190:191], 0x1e8481
	s_branch .LBB0_599

.LBB0_599:
	global_load_dword v198, v193, s[26:27] sc1
	s_memrealtime s[92:93]
	s_mov_b64 s[28:29], -1
	s_mov_b64 s[36:37], -1
	s_waitcnt vmcnt(0)
	v_readfirstlane_b32 s0, v198
	s_cmp_gt_u32 s0, 31
	s_cbranch_scc1 .LBB0_598
	s_waitcnt lgkmcnt(0)
	s_sub_u32 s28, s92, s18
	s_subb_u32 s29, s93, s19
	v_cmp_lt_u64_e32 vcc, s[28:29], v[190:191]
	s_cbranch_vccz .LBB0_597
	s_mov_b64 s[36:37], 0
	s_sleep 2
	s_branch .LBB0_597
.LBB0_602:
	s_waitcnt lgkmcnt(0)
	s_andn2_b64 vcc, exec, s[28:29]
	s_cbranch_vccz .LBB0_606
	s_mov_b64 s[18:19], 0
	s_and_saveexec_b64 s[26:27], s[10:11]
	s_cbranch_execz .LBB0_605
	s_and_b32 s0, s14, 0xbf
	s_or_b32 s0, s0, 0x740
	v_mov_b32_e32 v191, 0
	v_mov_b32_e32 v190, s0
	global_atomic_cmpswap v191, v[190:191], s[34:35] offset:4
	v_mov_b32_e32 v190, 1
	s_mov_b64 s[18:19], exec
	global_store_dword v191, v190, s[34:35] sc1

.LBB0_650:
	s_or_b64 exec, exec, s[12:13]
	s_andn2_b64 vcc, exec, s[20:21]
	s_cbranch_vccnz .LBB0_666
	s_memrealtime s[12:13]
	s_lshl_b32 s16, s14, 6
	s_ashr_i32 s17, s16, 31
	s_lshl_b64 s[16:17], s[16:17], 2
	s_add_u32 s16, s0, s16
	s_addc_u32 s17, s1, s17
	v_mov_b32_e32 v132, 0
	v_mov_b64_e32 v[130:131], 0x1e8481
	s_branch .LBB0_654

.LBB0_654:
	global_load_dword v133, v132, s[16:17] sc1
	s_memrealtime s[92:93]
	s_mov_b64 s[20:21], -1
	s_mov_b64 s[26:27], -1
	s_waitcnt vmcnt(0)
	v_readfirstlane_b32 s0, v133
	s_cmp_gt_u32 s0, 31
	s_cbranch_scc1 .LBB0_653
	s_waitcnt lgkmcnt(0)
	s_sub_u32 s0, s92, s12
	s_subb_u32 s1, s93, s13
	v_cmp_lt_u64_e32 vcc, s[0:1], v[130:131]
	s_cbranch_vccz .LBB0_652
	s_mov_b64 s[26:27], 0
	s_sleep 2
	s_branch .LBB0_652
.LBB0_657:
	s_waitcnt lgkmcnt(0)
	s_andn2_b64 vcc, exec, s[20:21]
	s_cbranch_vccz .LBB0_661
	s_mov_b64 s[12:13], 0
	s_and_saveexec_b64 s[16:17], s[10:11]
	s_cbranch_execz .LBB0_660
	s_and_b32 s0, s14, 0x7f
	s_or_b32 s0, s0, 0x780
	v_mov_b32_e32 v131, 0
	v_mov_b32_e32 v130, s0
	global_atomic_cmpswap v131, v[130:131], s[34:35] offset:4
	v_mov_b32_e32 v130, 1
	s_mov_b64 s[12:13], exec
	global_store_dword v131, v130, s[34:35] sc1

.LBB0_906:
	global_load_dword v190, v185, s[12:13] sc1
	s_memrealtime s[92:93]
	s_mov_b64 s[14:15], -1
	s_mov_b64 s[16:17], -1
	s_waitcnt vmcnt(0)
	v_readfirstlane_b32 s5, v190
	s_cmp_gt_u32 s5, 31
	s_cbranch_scc1 .LBB0_905
	s_waitcnt lgkmcnt(0)
	s_sub_u32 s14, s92, s10
	s_subb_u32 s15, s93, s11
	v_cmp_lt_u64_e32 vcc, s[14:15], v[182:183]
	s_cbranch_vccz .LBB0_904
	s_mov_b64 s[16:17], 0
	s_sleep 2
	s_branch .LBB0_904
.LBB0_909:
	s_waitcnt lgkmcnt(0)
	s_andn2_b64 vcc, exec, s[14:15]
	s_cbranch_vccz .LBB0_913
	s_waitcnt lgkmcnt(0)
	s_mov_b64 s[10:11], 0
	s_and_saveexec_b64 s[12:13], s[2:3]
	s_cbranch_execz .LBB0_912
	s_and_b32 s5, s29, 0xff
	s_or_b32 s5, s5, 0x700
	v_mov_b32_e32 v183, 0
	v_mov_b32_e32 v182, s5
	global_atomic_cmpswap v183, v[182:183], s[34:35] offset:4
	v_mov_b32_e32 v182, 1
	s_mov_b64 s[10:11], exec
	global_store_dword v183, v182, s[34:35] sc1
